# removes compiler asm-pad s_nop 0 between v_max3 ops (23 sites), on top of split packed f32 VALU + GEMM early-barrier + MLA loop rewrite + diff producer fusion
# speedup vs baseline: 1.0040x; 1.0040x over previous
; __device__ __forceinline__ float max3f(float a, float b, float c) { float r; asm("v_max3_f32 %0, %1, %2, %3" : "=v"(r) : "v"(a), "v"(b), "v"(c)); return r; }
; __device__ __forceinline__ float rowmax32(const f32x16& p0, const f32x16& p1) {
;     float a = max3f(p0[0], p0[1], p1[0]), b = max3f(p0[2], p0[3], p1[1]); a = max3f(a, p1[2], p1[3]);
; #pragma unroll
;     for (int r = 4; r < 16; r += 4) { a = max3f(a, p0[r], p0[r + 1]); b = max3f(b, p0[r + 2], p0[r + 3]); a = max3f(a, p1[r], p1[r + 1]); b = max3f(b, p1[r + 2], p1[r + 3]); }
;     return max3f(a, b, b);
; }
; __device__ __forceinline__ float attn_diff_pair(ALAS unsigned char* lds, const Args& A, int q0, f32x16 (&o)[4]) {
;     ...
;                 float mx = rowmax32(s0, s1);
;                 { auto rr = __builtin_amdgcn_permlane32_swap(__float_as_uint(mx), __float_as_uint(mx), false, false); mx = __builtin_fmaxf(__uint_as_float(rr[0]), __uint_as_float(rr[1])); }
;                 float alpha = 1.0f;
;                 if (__any(mx > mrun)) {
;                     const float mnew = __builtin_fmaxf(mrun, mx);
;                     alpha = __builtin_amdgcn_exp2f((mrun - mnew) * A.c1);
;                     mrun = mnew; lrun *= alpha;
; #pragma unroll
;                     for (int db = 0; db < 4; ++db)
; #pragma unroll
;                         for (int r = 0; r < 16; ++r) o[db][r] *= alpha;
;                 }
.LBB0_397:
	v_max3_f32 v0, v112, v113, v96
	v_max3_f32 v110, v114, v115, v97
	v_max3_f32 v0, v0, v98, v99
	v_max3_f32 v110, v110, v10, v11
	v_max3_f32 v0, v0, v14, v15
	v_max3_f32 v110, v110, v102, v103
	v_max3_f32 v0, v0, v100, v101
	v_max3_f32 v110, v110, v6, v7
	v_max3_f32 v0, v0, v8, v9
	v_max3_f32 v110, v110, v106, v107
	v_max3_f32 v0, v0, v104, v105
	v_max3_f32 v110, v110, v2, v3
	v_max3_f32 v0, v0, v4, v5
	v_max3_f32 v110, v110, v12, v13
	v_max3_f32 v0, v0, v108, v109
	v_max3_f32 v0, v0, v110, v110
	s_nop 0
	v_mov_b32_e32 v110, v0
	s_nop 1
	v_permlane32_swap_b32_e32 v0, v110
	v_max_f32_e32 v110, v110, v110
	v_max_f32_e32 v0, v0, v0
	v_max_f32_e32 v0, v0, v110
	v_cmp_gt_f32_e32 vcc, v0, v251
	s_cbranch_vccz .LBB0_399
	v_max_f32_e32 v0, v0, v0
	v_max_f32_e32 v110, v251, v251
	v_max_f32_e32 v110, v110, v0
	v_sub_f32_e32 v0, v251, v110
	v_mul_f32_e32 v0, 0x3e0293ee, v0
	v_exp_f32_e32 v0, v0
	v_mov_b32_e32 v251, v110
	v_pk_mul_f32 v[80:81], v[80:81], v[0:1] op_sel_hi:[1,0]
	v_pk_mul_f32 v[78:79], v[78:79], v[0:1] op_sel_hi:[1,0]
	v_pk_mul_f32 v[76:77], v[76:77], v[0:1] op_sel_hi:[1,0]
	v_pk_mul_f32 v[74:75], v[74:75], v[0:1] op_sel_hi:[1,0]
	v_pk_mul_f32 v[72:73], v[72:73], v[0:1] op_sel_hi:[1,0]
	v_pk_mul_f32 v[70:71], v[70:71], v[0:1] op_sel_hi:[1,0]
	v_pk_mul_f32 v[68:69], v[68:69], v[0:1] op_sel_hi:[1,0]
	v_pk_mul_f32 v[66:67], v[66:67], v[0:1] op_sel_hi:[1,0]
	v_pk_mul_f32 v[64:65], v[64:65], v[0:1] op_sel_hi:[1,0]
	v_pk_mul_f32 v[62:63], v[62:63], v[0:1] op_sel_hi:[1,0]
	v_pk_mul_f32 v[60:61], v[60:61], v[0:1] op_sel_hi:[1,0]
	v_pk_mul_f32 v[58:59], v[58:59], v[0:1] op_sel_hi:[1,0]
	v_pk_mul_f32 v[56:57], v[56:57], v[0:1] op_sel_hi:[1,0]
	v_pk_mul_f32 v[54:55], v[54:55], v[0:1] op_sel_hi:[1,0]
	v_pk_mul_f32 v[52:53], v[52:53], v[0:1] op_sel_hi:[1,0]
	v_pk_mul_f32 v[50:51], v[50:51], v[0:1] op_sel_hi:[1,0]
	v_pk_mul_f32 v[48:49], v[48:49], v[0:1] op_sel_hi:[1,0]
	v_pk_mul_f32 v[46:47], v[46:47], v[0:1] op_sel_hi:[1,0]
	v_pk_mul_f32 v[44:45], v[44:45], v[0:1] op_sel_hi:[1,0]
	v_pk_mul_f32 v[42:43], v[42:43], v[0:1] op_sel_hi:[1,0]
	v_pk_mul_f32 v[40:41], v[40:41], v[0:1] op_sel_hi:[1,0]
	v_pk_mul_f32 v[38:39], v[38:39], v[0:1] op_sel_hi:[1,0]
	v_pk_mul_f32 v[36:37], v[36:37], v[0:1] op_sel_hi:[1,0]
	v_pk_mul_f32 v[34:35], v[34:35], v[0:1] op_sel_hi:[1,0]
	v_pk_mul_f32 v[32:33], v[32:33], v[0:1] op_sel_hi:[1,0]
	v_pk_mul_f32 v[30:31], v[30:31], v[0:1] op_sel_hi:[1,0]
	v_pk_mul_f32 v[28:29], v[28:29], v[0:1] op_sel_hi:[1,0]
	v_pk_mul_f32 v[26:27], v[26:27], v[0:1] op_sel_hi:[1,0]
	v_pk_mul_f32 v[24:25], v[24:25], v[0:1] op_sel_hi:[1,0]
	v_pk_mul_f32 v[22:23], v[22:23], v[0:1] op_sel_hi:[1,0]
	v_pk_mul_f32 v[20:21], v[20:21], v[0:1] op_sel_hi:[1,0]
	v_pk_mul_f32 v[18:19], v[18:19], v[0:1] op_sel_hi:[1,0]
	v_mul_f32_e32 v250, v250, v0
	s_branch .LBB0_400

; __device__ __forceinline__ float max3f(float a, float b, float c) { float r; asm("v_max3_f32 %0, %1, %2, %3" : "=v"(r) : "v"(a), "v"(b), "v"(c)); return r; }
; __device__ __forceinline__ float rowmax32(const f32x16& p0, const f32x16& p1) {
;     float a = max3f(p0[0], p0[1], p1[0]), b = max3f(p0[2], p0[3], p1[1]); a = max3f(a, p1[2], p1[3]);
; #pragma unroll
;     for (int r = 4; r < 16; r += 4) { a = max3f(a, p0[r], p0[r + 1]); b = max3f(b, p0[r + 2], p0[r + 3]); a = max3f(a, p1[r], p1[r + 1]); b = max3f(b, p1[r + 2], p1[r + 3]); }
;     return max3f(a, b, b);
; }
; __device__ __forceinline__ float attn_mla_lag(ALAS unsigned char* lds, const Args& A, int q0, f32x16 (&o)[4]) {
;     ...
;             float mx = rowmax32(s0, s1);
;             { auto rr = __builtin_amdgcn_permlane32_swap(__float_as_uint(mx), __float_as_uint(mx), false, false); mx = __builtin_fmaxf(__uint_as_float(rr[0]), __uint_as_float(rr[1])); }
;             if (__any(mx > mrun)) {
;                 const float mnew = __builtin_fmaxf(mrun, mx);
;                 const float alpha = __builtin_amdgcn_exp2f((mrun - mnew) * A.c1);
;                 mrun = mnew; lrun *= alpha;
; #pragma unroll
;                 for (int db = 0; db < NDB; ++db)
; #pragma unroll
;                     for (int r = 0; r < 16; ++r) o[db][r] *= alpha;
;             }
.LBB0_1090:
	v_max3_f32 v0, v50, v51, v34
	v_max3_f32 v2, v52, v53, v35
	v_mov_b32_e32 v244, 0xf149f2ca
	v_max3_f32 v0, v0, v36, v37
	v_max3_f32 v2, v2, v56, v57
	v_max3_f32 v0, v0, v54, v55
	v_max3_f32 v2, v2, v40, v41
	v_max3_f32 v0, v0, v38, v39
	v_max3_f32 v2, v2, v60, v61
	v_max3_f32 v0, v0, v58, v59
	v_max3_f32 v2, v2, v44, v45
	v_max3_f32 v0, v0, v42, v43
	v_max3_f32 v2, v2, v64, v65
	v_max3_f32 v0, v0, v62, v63
	v_max3_f32 v2, v2, v48, v49
	v_max3_f32 v0, v0, v46, v47
	v_max3_f32 v0, v0, v2, v2
	s_nop 0
	v_mov_b32_e32 v2, v0
	s_nop 1
	v_permlane32_swap_b32_e32 v0, v2
	v_max_f32_e32 v2, v2, v2
	v_max_f32_e32 v0, v0, v0
	v_max_f32_e32 v0, v0, v2
	v_cmp_gt_f32_e32 vcc, v0, v244
	s_cbranch_vccz .LBB0_1092
	v_max_f32_e32 v0, v0, v0
	v_max_f32_e32 v244, 0xf149f2ca, v0
	v_sub_f32_e32 v0, 0xf149f2ca, v244
	v_mul_f32_e32 v0, 0x3dd53b94, v0
	v_exp_f32_e32 v0, v0
	s_nop 0
	v_mul_f32_e32 v18, 0, v0
	v_mov_b32_e32 v19, v18
	v_mov_b32_e32 v20, v18
	v_mov_b32_e32 v21, v18
	v_mov_b32_e32 v22, v18
	v_mov_b32_e32 v23, v18
	v_mov_b32_e32 v24, v18
	v_mov_b32_e32 v25, v18
	v_mov_b32_e32 v26, v18
	v_mov_b32_e32 v27, v18
	v_mov_b32_e32 v28, v18
	v_mov_b32_e32 v29, v18
	v_mov_b32_e32 v30, v18
	v_mov_b32_e32 v31, v18
	v_mov_b32_e32 v32, v18
	v_mov_b32_e32 v33, v18
	v_mov_b32_e32 v16, v18
	s_branch .LBB0_1093

; __device__ __forceinline__ float max3f(float a, float b, float c) { float r; asm("v_max3_f32 %0, %1, %2, %3" : "=v"(r) : "v"(a), "v"(b), "v"(c)); return r; }
; __device__ __forceinline__ float rowmax32(const f32x16& p0, const f32x16& p1) {
;     float a = max3f(p0[0], p0[1], p1[0]), b = max3f(p0[2], p0[3], p1[1]); a = max3f(a, p1[2], p1[3]);
; #pragma unroll
;     for (int r = 4; r < 16; r += 4) { a = max3f(a, p0[r], p0[r + 1]); b = max3f(b, p0[r + 2], p0[r + 3]); a = max3f(a, p1[r], p1[r + 1]); b = max3f(b, p1[r + 2], p1[r + 3]); }
;     return max3f(a, b, b);
; }
; __device__ __forceinline__ float attn_mla_lag(ALAS unsigned char* lds, const Args& A, int q0, f32x16 (&o)[4]) {
;     ...
;             float mx = rowmax32(s0, s1);
;             { auto rr = __builtin_amdgcn_permlane32_swap(__float_as_uint(mx), __float_as_uint(mx), false, false); mx = __builtin_fmaxf(__uint_as_float(rr[0]), __uint_as_float(rr[1])); }
;             if (__any(mx > mrun)) {
;                 const float mnew = __builtin_fmaxf(mrun, mx);
;                 const float alpha = __builtin_amdgcn_exp2f((mrun - mnew) * A.c1);
;                 mrun = mnew; lrun *= alpha;
; #pragma unroll
;                 for (int db = 0; db < NDB; ++db)
; #pragma unroll
;                     for (int r = 0; r < 16; ++r) o[db][r] *= alpha;
;             }
.LBB0_1119:
	v_max3_f32 v0, v66, v67, v82
	v_max3_f32 v146, v68, v69, v83
	v_max3_f32 v0, v0, v84, v85
	v_max3_f32 v146, v146, v72, v73
	v_max3_f32 v0, v0, v70, v71
	v_max3_f32 v146, v146, v88, v89
	v_max3_f32 v0, v0, v86, v87
	v_max3_f32 v146, v146, v76, v77
	v_max3_f32 v0, v0, v74, v75
	v_max3_f32 v146, v146, v92, v93
	v_max3_f32 v0, v0, v90, v91
	v_max3_f32 v146, v146, v80, v81
	v_max3_f32 v0, v0, v78, v79
	v_max3_f32 v146, v146, v96, v97
	v_max3_f32 v0, v0, v94, v95
	v_max3_f32 v0, v0, v146, v146
	s_nop 0
	v_mov_b32_e32 v146, v0
	s_nop 1
	v_permlane32_swap_b32_e32 v0, v146
	v_max_f32_e32 v146, v146, v146
	v_max_f32_e32 v0, v0, v0
	v_max_f32_e32 v0, v0, v146
	v_cmp_gt_f32_e32 vcc, v0, v244
	s_cbranch_vccz .LBB0_1121
	v_max_f32_e32 v0, v0, v0
	v_max_f32_e32 v146, v244, v244
	v_max_f32_e32 v146, v146, v0
	v_sub_f32_e32 v0, v244, v146
	v_mul_f32_e32 v0, 0x3dd53b94, v0
	v_exp_f32_e32 v0, v0
	v_mov_b32_e32 v244, v146
	v_mul_f32_e32 v243, v243, v0
	v_pk_mul_f32 v[32:33], v[0:1], v[32:33] op_sel_hi:[0,1]
	v_pk_mul_f32 v[30:31], v[0:1], v[30:31] op_sel_hi:[0,1]
	v_pk_mul_f32 v[28:29], v[0:1], v[28:29] op_sel_hi:[0,1]
	v_pk_mul_f32 v[26:27], v[0:1], v[26:27] op_sel_hi:[0,1]
	v_pk_mul_f32 v[24:25], v[0:1], v[24:25] op_sel_hi:[0,1]
	v_pk_mul_f32 v[22:23], v[0:1], v[22:23] op_sel_hi:[0,1]
	v_pk_mul_f32 v[20:21], v[0:1], v[20:21] op_sel_hi:[0,1]
	v_pk_mul_f32 v[18:19], v[0:1], v[18:19] op_sel_hi:[0,1]
	v_pk_mul_f32 v[64:65], v[0:1], v[64:65] op_sel_hi:[0,1]
	v_pk_mul_f32 v[62:63], v[0:1], v[62:63] op_sel_hi:[0,1]
	v_pk_mul_f32 v[60:61], v[0:1], v[60:61] op_sel_hi:[0,1]
	v_pk_mul_f32 v[58:59], v[0:1], v[58:59] op_sel_hi:[0,1]
	v_pk_mul_f32 v[56:57], v[0:1], v[56:57] op_sel_hi:[0,1]
	v_pk_mul_f32 v[54:55], v[0:1], v[54:55] op_sel_hi:[0,1]
	v_pk_mul_f32 v[52:53], v[0:1], v[52:53] op_sel_hi:[0,1]
	v_pk_mul_f32 v[50:51], v[0:1], v[50:51] op_sel_hi:[0,1]
	v_pk_mul_f32 v[48:49], v[0:1], v[48:49] op_sel_hi:[0,1]
	v_pk_mul_f32 v[46:47], v[0:1], v[46:47] op_sel_hi:[0,1]
	v_pk_mul_f32 v[44:45], v[0:1], v[44:45] op_sel_hi:[0,1]
	v_pk_mul_f32 v[42:43], v[0:1], v[42:43] op_sel_hi:[0,1]
	v_pk_mul_f32 v[40:41], v[0:1], v[40:41] op_sel_hi:[0,1]
	v_pk_mul_f32 v[38:39], v[0:1], v[38:39] op_sel_hi:[0,1]
	v_pk_mul_f32 v[36:37], v[0:1], v[36:37] op_sel_hi:[0,1]
	v_pk_mul_f32 v[34:35], v[0:1], v[34:35] op_sel_hi:[0,1]
	v_pk_mul_f32 v[16:17], v[0:1], v[16:17] op_sel_hi:[0,1]
	v_pk_mul_f32 v[14:15], v[0:1], v[14:15] op_sel_hi:[0,1]
	v_pk_mul_f32 v[12:13], v[0:1], v[12:13] op_sel_hi:[0,1]
	v_pk_mul_f32 v[10:11], v[0:1], v[10:11] op_sel_hi:[0,1]
	v_pk_mul_f32 v[8:9], v[0:1], v[8:9] op_sel_hi:[0,1]
	v_pk_mul_f32 v[6:7], v[0:1], v[6:7] op_sel_hi:[0,1]
	v_pk_mul_f32 v[4:5], v[0:1], v[4:5] op_sel_hi:[0,1]
	v_pk_mul_f32 v[2:3], v[0:1], v[2:3] op_sel_hi:[0,1]
